# static s_setprio 1 for waves 0-3 (instead of 4-7) for the duration of the differential-attention phase
# speedup vs baseline: 1.0038x; 1.0038x over previous
.LBB0_417:
	s_and_b64 vcc, exec, s[6:7]
	s_cbranch_vccz .LBB0_700
	s_cmp_gt_i32 s34, 1
	s_mov_b64 s[6:7], -1
	s_cbranch_scc0 .LBB0_579
	v_mov_b32_e32 v224, v234
	v_writelane_b32 v255, s34, 32
	s_mov_b32 s44, 0
	v_readfirstlane_b32 s0, v224
	s_nop 1
	v_writelane_b32 v255, s0, 33
	s_cmp_ge_u32 s0, 0x100
	s_cbranch_scc1 .Lattn_prio_done
	s_setprio 1
